# rot4
# speedup vs baseline: 1.0024x; 1.0024x over previous
.LBB0_250:
	s_ashr_i32 s47, s46, 31
	s_lshl_b64 s[48:49], s[46:47], 20
	v_readlane_b32 s26, v254, 61
	s_add_u32 s48, s26, s48
	v_readlane_b32 s26, v254, 62
	s_addc_u32 s49, s26, s49
	s_and_b64 s[50:51], s[38:39], exec
	s_cselect_b32 s26, s49, s63
	s_cselect_b32 s47, s48, s62
	s_ashr_i32 s45, s44, 31
	s_lshl_b64 s[50:51], s[44:45], 20
	s_add_u32 s50, s6, s50
	s_addc_u32 s51, s9, s51
	s_and_b64 s[64:65], s[38:39], exec
	s_cselect_b32 s45, s51, s61
	s_cselect_b32 s72, s50, s60
	s_add_u32 s73, s60, 0x100
	s_addc_u32 s76, s61, 0
	s_add_u32 s60, s62, 0x80080
	v_mov_b32_e32 v2, 0
	s_addc_u32 s61, s63, 0
	s_mov_b32 s77, -2
	v_mov_b32_e32 v3, v2
	v_mov_b32_e32 v4, v2
	v_mov_b32_e32 v5, v2
	v_mov_b32_e32 v6, v2
	v_mov_b32_e32 v7, v2
	v_mov_b32_e32 v8, v2
	v_mov_b32_e32 v9, v2
	v_mov_b32_e32 v14, v2
	v_mov_b32_e32 v15, v2
	v_mov_b32_e32 v16, v2
	v_mov_b32_e32 v17, v2
	v_mov_b32_e32 v22, v2
	v_mov_b32_e32 v23, v2
	v_mov_b32_e32 v24, v2
	v_mov_b32_e32 v25, v2
	v_mov_b32_e32 v30, v2
	v_mov_b32_e32 v31, v2
	v_mov_b32_e32 v32, v2
	v_mov_b32_e32 v33, v2
	v_mov_b32_e32 v38, v2
	v_mov_b32_e32 v39, v2
	v_mov_b32_e32 v40, v2
	v_mov_b32_e32 v41, v2
	v_mov_b32_e32 v46, v2
	v_mov_b32_e32 v47, v2
	v_mov_b32_e32 v48, v2
	v_mov_b32_e32 v49, v2
	v_mov_b32_e32 v54, v2
	v_mov_b32_e32 v55, v2
	v_mov_b32_e32 v56, v2
	v_mov_b32_e32 v57, v2
	v_mov_b32_e32 v10, v2
	v_mov_b32_e32 v11, v2
	v_mov_b32_e32 v12, v2
	v_mov_b32_e32 v13, v2
	v_mov_b32_e32 v18, v2
	v_mov_b32_e32 v19, v2
	v_mov_b32_e32 v20, v2
	v_mov_b32_e32 v21, v2
	v_mov_b32_e32 v26, v2
	v_mov_b32_e32 v27, v2
	v_mov_b32_e32 v28, v2
	v_mov_b32_e32 v29, v2
	v_mov_b32_e32 v34, v2
	v_mov_b32_e32 v35, v2
	v_mov_b32_e32 v36, v2
	v_mov_b32_e32 v37, v2
	v_mov_b32_e32 v42, v2
	v_mov_b32_e32 v43, v2
	v_mov_b32_e32 v44, v2
	v_mov_b32_e32 v45, v2
	v_mov_b32_e32 v50, v2
	v_mov_b32_e32 v51, v2
	v_mov_b32_e32 v52, v2
	v_mov_b32_e32 v53, v2
	v_mov_b32_e32 v58, v2
	v_mov_b32_e32 v59, v2
	v_mov_b32_e32 v60, v2
	v_mov_b32_e32 v61, v2
	v_mov_b32_e32 v62, v2
	v_mov_b32_e32 v63, v2
	v_mov_b32_e32 v64, v2
	v_mov_b32_e32 v65, v2
	v_mov_b32_e32 v66, v2
	v_mov_b32_e32 v67, v2
	v_mov_b32_e32 v68, v2
	v_mov_b32_e32 v69, v2
	v_mov_b32_e32 v70, v2
	v_mov_b32_e32 v71, v2
	v_mov_b32_e32 v72, v2
	v_mov_b32_e32 v73, v2
	v_mov_b32_e32 v78, v2
	v_mov_b32_e32 v79, v2
	v_mov_b32_e32 v80, v2
	v_mov_b32_e32 v81, v2
	v_mov_b32_e32 v86, v2
	v_mov_b32_e32 v87, v2
	v_mov_b32_e32 v88, v2
	v_mov_b32_e32 v89, v2
	v_mov_b32_e32 v94, v2
	v_mov_b32_e32 v95, v2
	v_mov_b32_e32 v96, v2
	v_mov_b32_e32 v97, v2
	v_mov_b32_e32 v102, v2
	v_mov_b32_e32 v103, v2
	v_mov_b32_e32 v104, v2
	v_mov_b32_e32 v105, v2
	v_mov_b32_e32 v110, v2
	v_mov_b32_e32 v111, v2
	v_mov_b32_e32 v112, v2
	v_mov_b32_e32 v113, v2
	v_mov_b32_e32 v118, v2
	v_mov_b32_e32 v119, v2
	v_mov_b32_e32 v120, v2
	v_mov_b32_e32 v121, v2
	v_mov_b32_e32 v74, v2
	v_mov_b32_e32 v75, v2
	v_mov_b32_e32 v76, v2
	v_mov_b32_e32 v77, v2
	v_mov_b32_e32 v82, v2
	v_mov_b32_e32 v83, v2
	v_mov_b32_e32 v84, v2
	v_mov_b32_e32 v85, v2
	v_mov_b32_e32 v90, v2
	v_mov_b32_e32 v91, v2
	v_mov_b32_e32 v92, v2
	v_mov_b32_e32 v93, v2
	v_mov_b32_e32 v98, v2
	v_mov_b32_e32 v99, v2
	v_mov_b32_e32 v100, v2
	v_mov_b32_e32 v101, v2
	v_mov_b32_e32 v106, v2
	v_mov_b32_e32 v107, v2
	v_mov_b32_e32 v108, v2
	v_mov_b32_e32 v109, v2
	v_mov_b32_e32 v114, v2
	v_mov_b32_e32 v115, v2
	v_mov_b32_e32 v116, v2
	v_mov_b32_e32 v117, v2
	v_mov_b32_e32 v122, v2
	v_mov_b32_e32 v123, v2
	v_mov_b32_e32 v124, v2
	v_mov_b32_e32 v125, v2
	v_mov_b32_e32 v126, v2
	v_mov_b32_e32 v127, v2
	v_mov_b32_e32 v128, v2
	v_mov_b32_e32 v129, v2
	s_add_u32 s62, s60, 0xfff80080
	s_addc_u32 s63, s61, -1
	s_cmp_eq_u32 s77, 28
	s_cselect_b32 s65, s26, s63
	s_cselect_b32 s64, s47, s62
	s_cselect_b32 s63, s45, s76
	s_cselect_b32 s62, s72, s73
.LBB0_251:
	s_add_i32 s78, 0, 0x10000
	v_add_u32_e32 v0, s78, v143
	s_add_i32 s80, 0, 0x14000
	ds_read_b128 v[146:149], v0
	ds_read_b128 v[150:153], v0 offset:1024
	ds_read_b128 v[154:157], v0 offset:2048
	ds_read_b128 v[158:161], v0 offset:3072
	v_add_u32_e32 v0, s80, v143
	ds_read_b128 v[162:165], v0
	ds_read_b128 v[176:179], v0 offset:1024
	ds_read_b128 v[180:183], v0 offset:2048
	ds_read_b128 v[184:187], v0 offset:3072
	v_lshl_add_u64 v[140:141], s[60:61], 0, v[138:139]
	s_add_i32 m0, s22, 0xc000
	ds_read_b128 v[188:191], v144
	ds_read_b128 v[192:195], v144 offset:1024
	ds_read_b128 v[196:199], v144 offset:2048
	ds_read_b128 v[200:203], v144 offset:3072
	ds_read_b128 v[204:207], v144 offset:4096
	ds_read_b128 v[208:211], v144 offset:5120
	ds_read_b128 v[224:227], v144 offset:6144
	ds_read_b128 v[228:231], v144 offset:7168
	global_load_lds_dwordx4 v[140:141], off
	v_lshl_add_u64 v[140:141], s[60:61], 0, v[136:137]
	s_add_i32 m0, s22, 0xe000
	s_nop 0
	global_load_lds_dwordx4 v[140:141], off
	s_waitcnt vmcnt(8)
	s_waitcnt lgkmcnt(0)
	s_barrier
	s_setprio 1
	s_waitcnt lgkmcnt(0)
	v_mfma_f32_16x16x32_bf16 v[126:129], v[146:149], v[188:191], v[126:129]
	v_mfma_f32_16x16x32_bf16 v[122:125], v[154:157], v[188:191], v[122:125]
	v_mfma_f32_16x16x32_bf16 v[114:117], v[146:149], v[196:199], v[114:117]
	v_mfma_f32_16x16x32_bf16 v[106:109], v[154:157], v[196:199], v[106:109]
	v_mfma_f32_16x16x32_bf16 v[98:101], v[146:149], v[204:207], v[98:101]
	v_mfma_f32_16x16x32_bf16 v[90:93], v[154:157], v[204:207], v[90:93]
	v_mfma_f32_16x16x32_bf16 v[82:85], v[146:149], v[224:227], v[82:85]
	v_mfma_f32_16x16x32_bf16 v[74:77], v[154:157], v[224:227], v[74:77]
	v_mfma_f32_16x16x32_bf16 v[126:129], v[150:153], v[192:195], v[126:129]
	v_mfma_f32_16x16x32_bf16 v[122:125], v[158:161], v[192:195], v[122:125]
	v_mfma_f32_16x16x32_bf16 v[114:117], v[150:153], v[200:203], v[114:117]
	v_mfma_f32_16x16x32_bf16 v[106:109], v[158:161], v[200:203], v[106:109]
	v_mfma_f32_16x16x32_bf16 v[98:101], v[150:153], v[208:211], v[98:101]
	v_mfma_f32_16x16x32_bf16 v[90:93], v[158:161], v[208:211], v[90:93]
	v_mfma_f32_16x16x32_bf16 v[82:85], v[150:153], v[228:231], v[82:85]
	v_mfma_f32_16x16x32_bf16 v[74:77], v[158:161], v[228:231], v[74:77]
	s_setprio 0
	s_setprio 1
	v_mfma_f32_16x16x32_bf16 v[118:121], v[162:165], v[188:191], v[118:121]
	v_mfma_f32_16x16x32_bf16 v[110:113], v[180:183], v[188:191], v[110:113]
	v_mfma_f32_16x16x32_bf16 v[102:105], v[162:165], v[196:199], v[102:105]
	v_mfma_f32_16x16x32_bf16 v[94:97], v[180:183], v[196:199], v[94:97]
	v_mfma_f32_16x16x32_bf16 v[86:89], v[162:165], v[204:207], v[86:89]
	v_mfma_f32_16x16x32_bf16 v[78:81], v[180:183], v[204:207], v[78:81]
	v_mfma_f32_16x16x32_bf16 v[70:73], v[162:165], v[224:227], v[70:73]
	v_mfma_f32_16x16x32_bf16 v[66:69], v[180:183], v[224:227], v[66:69]
	v_mfma_f32_16x16x32_bf16 v[118:121], v[176:179], v[192:195], v[118:121]
	v_mfma_f32_16x16x32_bf16 v[110:113], v[184:187], v[192:195], v[110:113]
	v_mfma_f32_16x16x32_bf16 v[102:105], v[176:179], v[200:203], v[102:105]
	v_mfma_f32_16x16x32_bf16 v[94:97], v[184:187], v[200:203], v[94:97]
	v_mfma_f32_16x16x32_bf16 v[86:89], v[176:179], v[208:211], v[86:89]
	v_mfma_f32_16x16x32_bf16 v[78:81], v[184:187], v[208:211], v[78:81]
	v_mfma_f32_16x16x32_bf16 v[70:73], v[176:179], v[228:231], v[70:73]
	v_mfma_f32_16x16x32_bf16 v[66:69], v[184:187], v[228:231], v[66:69]
	s_setprio 0
	s_barrier
	s_add_i32 s78, s78, s14
	v_lshl_add_u64 v[140:141], s[62:63], 0, v[132:133]
	s_mov_b32 m0, s78
	ds_read_b128 v[188:191], v144 offset:16384
	ds_read_b128 v[192:195], v144 offset:17408
	ds_read_b128 v[196:199], v144 offset:18432
	ds_read_b128 v[200:203], v144 offset:19456
	ds_read_b128 v[204:207], v144 offset:20480
	ds_read_b128 v[208:211], v144 offset:21504
	ds_read_b128 v[224:227], v144 offset:22528
	ds_read_b128 v[228:231], v144 offset:23552
	global_load_lds_dwordx4 v[140:141], off
	s_add_i32 m0, s78, 0x2000
	s_add_u32 s78, s62, 0x80000
	v_lshl_add_u64 v[168:169], s[62:63], 0, v[130:131]
	s_addc_u32 s79, s63, 0
	s_add_i32 s80, s80, s14
	global_load_lds_dwordx4 v[168:169], off
	v_lshl_add_u64 v[170:171], s[78:79], 0, v[132:133]
	s_mov_b32 m0, s80
	v_lshl_add_u64 v[172:173], s[64:65], 0, v[130:131]
	global_load_lds_dwordx4 v[170:171], off
	v_lshl_add_u64 v[170:171], s[78:79], 0, v[130:131]
	s_add_i32 m0, s80, 0x2000
	s_nop 0
	global_load_lds_dwordx4 v[170:171], off
	v_lshl_add_u64 v[170:171], s[64:65], 0, v[132:133]
	s_mov_b32 m0, s22
	s_nop 0
	global_load_lds_dwordx4 v[170:171], off
	s_mov_b32 m0, s23
	s_nop 0
	global_load_lds_dwordx4 v[172:173], off
	s_waitcnt vmcnt(8)
	s_waitcnt lgkmcnt(0)
	s_barrier
	s_setprio 1
	s_waitcnt lgkmcnt(0)
	v_mfma_f32_16x16x32_bf16 v[62:65], v[146:149], v[188:191], v[62:65]
	v_mfma_f32_16x16x32_bf16 v[58:61], v[154:157], v[188:191], v[58:61]
	v_mfma_f32_16x16x32_bf16 v[50:53], v[146:149], v[196:199], v[50:53]
	v_mfma_f32_16x16x32_bf16 v[42:45], v[154:157], v[196:199], v[42:45]
	v_mfma_f32_16x16x32_bf16 v[34:37], v[146:149], v[204:207], v[34:37]
	v_mfma_f32_16x16x32_bf16 v[26:29], v[154:157], v[204:207], v[26:29]
	v_mfma_f32_16x16x32_bf16 v[18:21], v[146:149], v[224:227], v[18:21]
	v_mfma_f32_16x16x32_bf16 v[10:13], v[154:157], v[224:227], v[10:13]
	v_mfma_f32_16x16x32_bf16 v[62:65], v[150:153], v[192:195], v[62:65]
	v_mfma_f32_16x16x32_bf16 v[58:61], v[158:161], v[192:195], v[58:61]
	v_mfma_f32_16x16x32_bf16 v[50:53], v[150:153], v[200:203], v[50:53]
	v_mfma_f32_16x16x32_bf16 v[42:45], v[158:161], v[200:203], v[42:45]
	v_mfma_f32_16x16x32_bf16 v[34:37], v[150:153], v[208:211], v[34:37]
	v_mfma_f32_16x16x32_bf16 v[26:29], v[158:161], v[208:211], v[26:29]
	v_mfma_f32_16x16x32_bf16 v[18:21], v[150:153], v[228:231], v[18:21]
	v_mfma_f32_16x16x32_bf16 v[10:13], v[158:161], v[228:231], v[10:13]
	s_setprio 0
	s_setprio 1
	v_mfma_f32_16x16x32_bf16 v[54:57], v[162:165], v[188:191], v[54:57]
	v_mfma_f32_16x16x32_bf16 v[46:49], v[180:183], v[188:191], v[46:49]
	v_mfma_f32_16x16x32_bf16 v[38:41], v[162:165], v[196:199], v[38:41]
	v_mfma_f32_16x16x32_bf16 v[30:33], v[180:183], v[196:199], v[30:33]
	v_mfma_f32_16x16x32_bf16 v[22:25], v[162:165], v[204:207], v[22:25]
	v_mfma_f32_16x16x32_bf16 v[14:17], v[180:183], v[204:207], v[14:17]
	v_mfma_f32_16x16x32_bf16 v[6:9], v[162:165], v[224:227], v[6:9]
	v_mfma_f32_16x16x32_bf16 v[2:5], v[180:183], v[224:227], v[2:5]
	v_mfma_f32_16x16x32_bf16 v[54:57], v[176:179], v[192:195], v[54:57]
	v_mfma_f32_16x16x32_bf16 v[46:49], v[184:187], v[192:195], v[46:49]
	v_mfma_f32_16x16x32_bf16 v[38:41], v[176:179], v[200:203], v[38:41]
	v_mfma_f32_16x16x32_bf16 v[30:33], v[184:187], v[200:203], v[30:33]
	v_mfma_f32_16x16x32_bf16 v[22:25], v[176:179], v[208:211], v[22:25]
	v_mfma_f32_16x16x32_bf16 v[14:17], v[184:187], v[208:211], v[14:17]
	v_mfma_f32_16x16x32_bf16 v[6:9], v[176:179], v[228:231], v[6:9]
	v_mfma_f32_16x16x32_bf16 v[2:5], v[184:187], v[228:231], v[2:5]
	s_setprio 0
	s_barrier
	s_add_i32 s78, 0, 0x18000
	v_add_u32_e32 v0, s78, v143
	s_add_i32 s79, 0, 0x1c000
	ds_read_b128 v[146:149], v0
	ds_read_b128 v[150:153], v0 offset:1024
	ds_read_b128 v[154:157], v0 offset:2048
	ds_read_b128 v[158:161], v0 offset:3072
	v_add_u32_e32 v0, s79, v143
	ds_read_b128 v[162:165], v0
	ds_read_b128 v[176:179], v0 offset:1024
	ds_read_b128 v[180:183], v0 offset:2048
	ds_read_b128 v[184:187], v0 offset:3072
	s_add_u32 s64, s64, 0x80000
	s_addc_u32 s65, s65, 0
	s_mov_b32 m0, s66
	v_lshl_add_u64 v[212:213], s[64:65], 0, v[132:133]
	ds_read_b128 v[188:191], v144 offset:32768
	ds_read_b128 v[192:195], v144 offset:33792
	ds_read_b128 v[196:199], v144 offset:34816
	ds_read_b128 v[200:203], v144 offset:35840
	ds_read_b128 v[204:207], v144 offset:36864
	ds_read_b128 v[208:211], v144 offset:37888
	ds_read_b128 v[224:227], v144 offset:38912
	ds_read_b128 v[228:231], v144 offset:39936
	global_load_lds_dwordx4 v[212:213], off
	v_lshl_add_u64 v[212:213], s[64:65], 0, v[130:131]
	s_mov_b32 m0, s67
	s_nop 0
	global_load_lds_dwordx4 v[212:213], off
	s_waitcnt vmcnt(8)
	s_waitcnt lgkmcnt(0)
	s_barrier
	s_setprio 1
	s_waitcnt lgkmcnt(0)
	v_mfma_f32_16x16x32_bf16 v[126:129], v[146:149], v[188:191], v[126:129]
	v_mfma_f32_16x16x32_bf16 v[122:125], v[154:157], v[188:191], v[122:125]
	v_mfma_f32_16x16x32_bf16 v[114:117], v[146:149], v[196:199], v[114:117]
	v_mfma_f32_16x16x32_bf16 v[106:109], v[154:157], v[196:199], v[106:109]
	v_mfma_f32_16x16x32_bf16 v[98:101], v[146:149], v[204:207], v[98:101]
	v_mfma_f32_16x16x32_bf16 v[90:93], v[154:157], v[204:207], v[90:93]
	v_mfma_f32_16x16x32_bf16 v[82:85], v[146:149], v[224:227], v[82:85]
	v_mfma_f32_16x16x32_bf16 v[74:77], v[154:157], v[224:227], v[74:77]
	v_mfma_f32_16x16x32_bf16 v[126:129], v[150:153], v[192:195], v[126:129]
	v_mfma_f32_16x16x32_bf16 v[122:125], v[158:161], v[192:195], v[122:125]
	v_mfma_f32_16x16x32_bf16 v[114:117], v[150:153], v[200:203], v[114:117]
	v_mfma_f32_16x16x32_bf16 v[106:109], v[158:161], v[200:203], v[106:109]
	v_mfma_f32_16x16x32_bf16 v[98:101], v[150:153], v[208:211], v[98:101]
	v_mfma_f32_16x16x32_bf16 v[90:93], v[158:161], v[208:211], v[90:93]
	v_mfma_f32_16x16x32_bf16 v[82:85], v[150:153], v[228:231], v[82:85]
	v_mfma_f32_16x16x32_bf16 v[74:77], v[158:161], v[228:231], v[74:77]
	s_setprio 0
	s_setprio 1
	v_mfma_f32_16x16x32_bf16 v[118:121], v[162:165], v[188:191], v[118:121]
	v_mfma_f32_16x16x32_bf16 v[110:113], v[180:183], v[188:191], v[110:113]
	v_mfma_f32_16x16x32_bf16 v[102:105], v[162:165], v[196:199], v[102:105]
	v_mfma_f32_16x16x32_bf16 v[94:97], v[180:183], v[196:199], v[94:97]
	v_mfma_f32_16x16x32_bf16 v[86:89], v[162:165], v[204:207], v[86:89]
	v_mfma_f32_16x16x32_bf16 v[78:81], v[180:183], v[204:207], v[78:81]
	v_mfma_f32_16x16x32_bf16 v[70:73], v[162:165], v[224:227], v[70:73]
	v_mfma_f32_16x16x32_bf16 v[66:69], v[180:183], v[224:227], v[66:69]
	v_mfma_f32_16x16x32_bf16 v[118:121], v[176:179], v[192:195], v[118:121]
	v_mfma_f32_16x16x32_bf16 v[110:113], v[184:187], v[192:195], v[110:113]
	v_mfma_f32_16x16x32_bf16 v[102:105], v[176:179], v[200:203], v[102:105]
	v_mfma_f32_16x16x32_bf16 v[94:97], v[184:187], v[200:203], v[94:97]
	v_mfma_f32_16x16x32_bf16 v[86:89], v[176:179], v[208:211], v[86:89]
	v_mfma_f32_16x16x32_bf16 v[78:81], v[184:187], v[208:211], v[78:81]
	v_mfma_f32_16x16x32_bf16 v[70:73], v[176:179], v[228:231], v[70:73]
	v_mfma_f32_16x16x32_bf16 v[66:69], v[184:187], v[228:231], v[66:69]
	s_setprio 0
	s_barrier
	s_add_i32 s64, s78, s14
	v_lshl_add_u64 v[140:141], v[140:141], 0, s[54:55]
	s_mov_b32 m0, s64
	ds_read_b128 v[188:191], v144 offset:49152
	ds_read_b128 v[192:195], v144 offset:50176
	ds_read_b128 v[196:199], v144 offset:51200
	ds_read_b128 v[200:203], v144 offset:52224
	ds_read_b128 v[204:207], v144 offset:53248
	ds_read_b128 v[208:211], v144 offset:54272
	ds_read_b128 v[224:227], v144 offset:55296
	ds_read_b128 v[228:231], v144 offset:56320
	global_load_lds_dwordx4 v[140:141], off
	s_add_i32 m0, s64, 0x2000
	s_add_u32 s62, s62, 0x80080
	v_lshl_add_u64 v[140:141], v[168:169], 0, s[54:55]
	s_addc_u32 s63, s63, 0
	s_add_i32 s64, s79, s14
	global_load_lds_dwordx4 v[140:141], off
	v_lshl_add_u64 v[140:141], s[62:63], 0, v[132:133]
	s_mov_b32 m0, s64
	s_nop 0
	global_load_lds_dwordx4 v[140:141], off
	v_lshl_add_u64 v[140:141], s[62:63], 0, v[130:131]
	s_add_i32 m0, s64, 0x2000
	s_nop 0
	global_load_lds_dwordx4 v[140:141], off
	v_lshl_add_u64 v[140:141], v[170:171], 0, s[54:55]
	s_mov_b32 m0, s69
	s_nop 0
	global_load_lds_dwordx4 v[140:141], off
	v_lshl_add_u64 v[140:141], v[172:173], 0, s[54:55]
	s_mov_b32 m0, s70
	s_nop 0
	global_load_lds_dwordx4 v[140:141], off
	s_add_i32 s77, s77, 2
	s_add_u32 s73, s73, 0x100
	s_addc_u32 s76, s76, 0
	s_add_u32 s60, s60, 0x100
	s_addc_u32 s61, s61, 0
	s_add_u32 s62, s60, 0xfff80080
	s_addc_u32 s63, s61, -1
	s_cmp_eq_u32 s77, 28
	s_cselect_b32 s65, s26, s63
	s_cselect_b32 s64, s47, s62
	s_cselect_b32 s63, s45, s76
	s_cselect_b32 s62, s72, s73
	s_waitcnt vmcnt(8)
	s_waitcnt lgkmcnt(0)
	s_barrier
	s_setprio 1
	s_waitcnt lgkmcnt(0)
	v_mfma_f32_16x16x32_bf16 v[62:65], v[146:149], v[188:191], v[62:65]
	v_mfma_f32_16x16x32_bf16 v[58:61], v[154:157], v[188:191], v[58:61]
	v_mfma_f32_16x16x32_bf16 v[50:53], v[146:149], v[196:199], v[50:53]
	v_mfma_f32_16x16x32_bf16 v[42:45], v[154:157], v[196:199], v[42:45]
	v_mfma_f32_16x16x32_bf16 v[34:37], v[146:149], v[204:207], v[34:37]
	v_mfma_f32_16x16x32_bf16 v[26:29], v[154:157], v[204:207], v[26:29]
	v_mfma_f32_16x16x32_bf16 v[18:21], v[146:149], v[224:227], v[18:21]
	v_mfma_f32_16x16x32_bf16 v[10:13], v[154:157], v[224:227], v[10:13]
	v_mfma_f32_16x16x32_bf16 v[62:65], v[150:153], v[192:195], v[62:65]
	v_mfma_f32_16x16x32_bf16 v[58:61], v[158:161], v[192:195], v[58:61]
	v_mfma_f32_16x16x32_bf16 v[50:53], v[150:153], v[200:203], v[50:53]
	v_mfma_f32_16x16x32_bf16 v[42:45], v[158:161], v[200:203], v[42:45]
	v_mfma_f32_16x16x32_bf16 v[34:37], v[150:153], v[208:211], v[34:37]
	v_mfma_f32_16x16x32_bf16 v[26:29], v[158:161], v[208:211], v[26:29]
	v_mfma_f32_16x16x32_bf16 v[18:21], v[150:153], v[228:231], v[18:21]
	v_mfma_f32_16x16x32_bf16 v[10:13], v[158:161], v[228:231], v[10:13]
	s_setprio 0
	s_setprio 1
	v_mfma_f32_16x16x32_bf16 v[54:57], v[162:165], v[188:191], v[54:57]
	v_mfma_f32_16x16x32_bf16 v[46:49], v[180:183], v[188:191], v[46:49]
	v_mfma_f32_16x16x32_bf16 v[38:41], v[162:165], v[196:199], v[38:41]
	v_mfma_f32_16x16x32_bf16 v[30:33], v[180:183], v[196:199], v[30:33]
	v_mfma_f32_16x16x32_bf16 v[22:25], v[162:165], v[204:207], v[22:25]
	v_mfma_f32_16x16x32_bf16 v[14:17], v[180:183], v[204:207], v[14:17]
	v_mfma_f32_16x16x32_bf16 v[6:9], v[162:165], v[224:227], v[6:9]
	v_mfma_f32_16x16x32_bf16 v[2:5], v[180:183], v[224:227], v[2:5]
	v_mfma_f32_16x16x32_bf16 v[54:57], v[176:179], v[192:195], v[54:57]
	v_mfma_f32_16x16x32_bf16 v[46:49], v[184:187], v[192:195], v[46:49]
	v_mfma_f32_16x16x32_bf16 v[38:41], v[176:179], v[200:203], v[38:41]
	v_mfma_f32_16x16x32_bf16 v[30:33], v[184:187], v[200:203], v[30:33]
	v_mfma_f32_16x16x32_bf16 v[22:25], v[176:179], v[208:211], v[22:25]
	v_mfma_f32_16x16x32_bf16 v[14:17], v[184:187], v[208:211], v[14:17]
	v_mfma_f32_16x16x32_bf16 v[6:9], v[176:179], v[228:231], v[6:9]
	v_mfma_f32_16x16x32_bf16 v[2:5], v[184:187], v[228:231], v[2:5]
	s_setprio 0
	s_barrier
	s_cmp_gt_u32 s77, 29
	s_cbranch_scc0 .LBB0_251
	s_and_b64 vcc, exec, s[42:43]
	s_cbranch_vccz .LBB0_254
	s_barrier

.LBB0_324:
	s_ashr_i32 s43, s42, 31
	s_lshl_b64 s[48:49], s[42:43], 18
	s_add_u32 s48, s9, s48
	s_addc_u32 s49, s14, s49
	s_and_b64 s[50:51], s[38:39], exec
	s_cselect_b32 s43, s49, s61
	s_cselect_b32 s47, s48, s60
	s_ashr_i32 s45, s44, 31
	s_lshl_b64 s[50:51], s[44:45], 18
	s_add_u32 s50, s17, s50
	s_addc_u32 s51, s22, s51
	s_and_b64 s[62:63], s[38:39], exec
	s_cselect_b32 s45, s51, s53
	s_cselect_b32 s72, s50, s52
	s_add_u32 s73, s52, 0x100
	s_addc_u32 s76, s53, 0
	s_add_u32 s52, s60, 0x20080
	v_mov_b32_e32 v2, 0
	s_addc_u32 s53, s61, 0
	s_mov_b32 s77, -2
	v_mov_b32_e32 v3, v2
	v_mov_b32_e32 v4, v2
	v_mov_b32_e32 v5, v2
	v_mov_b32_e32 v6, v2
	v_mov_b32_e32 v7, v2
	v_mov_b32_e32 v8, v2
	v_mov_b32_e32 v9, v2
	v_mov_b32_e32 v10, v2
	v_mov_b32_e32 v11, v2
	v_mov_b32_e32 v12, v2
	v_mov_b32_e32 v13, v2
	v_mov_b32_e32 v18, v2
	v_mov_b32_e32 v19, v2
	v_mov_b32_e32 v20, v2
	v_mov_b32_e32 v21, v2
	v_mov_b32_e32 v26, v2
	v_mov_b32_e32 v27, v2
	v_mov_b32_e32 v28, v2
	v_mov_b32_e32 v29, v2
	v_mov_b32_e32 v34, v2
	v_mov_b32_e32 v35, v2
	v_mov_b32_e32 v36, v2
	v_mov_b32_e32 v37, v2
	v_mov_b32_e32 v42, v2
	v_mov_b32_e32 v43, v2
	v_mov_b32_e32 v44, v2
	v_mov_b32_e32 v45, v2
	v_mov_b32_e32 v50, v2
	v_mov_b32_e32 v51, v2
	v_mov_b32_e32 v52, v2
	v_mov_b32_e32 v53, v2
	v_mov_b32_e32 v14, v2
	v_mov_b32_e32 v15, v2
	v_mov_b32_e32 v16, v2
	v_mov_b32_e32 v17, v2
	v_mov_b32_e32 v22, v2
	v_mov_b32_e32 v23, v2
	v_mov_b32_e32 v24, v2
	v_mov_b32_e32 v25, v2
	v_mov_b32_e32 v30, v2
	v_mov_b32_e32 v31, v2
	v_mov_b32_e32 v32, v2
	v_mov_b32_e32 v33, v2
	v_mov_b32_e32 v38, v2
	v_mov_b32_e32 v39, v2
	v_mov_b32_e32 v40, v2
	v_mov_b32_e32 v41, v2
	v_mov_b32_e32 v46, v2
	v_mov_b32_e32 v47, v2
	v_mov_b32_e32 v48, v2
	v_mov_b32_e32 v49, v2
	v_mov_b32_e32 v54, v2
	v_mov_b32_e32 v55, v2
	v_mov_b32_e32 v56, v2
	v_mov_b32_e32 v57, v2
	v_mov_b32_e32 v58, v2
	v_mov_b32_e32 v59, v2
	v_mov_b32_e32 v60, v2
	v_mov_b32_e32 v61, v2
	v_mov_b32_e32 v62, v2
	v_mov_b32_e32 v63, v2
	v_mov_b32_e32 v64, v2
	v_mov_b32_e32 v65, v2
	v_mov_b32_e32 v66, v2
	v_mov_b32_e32 v67, v2
	v_mov_b32_e32 v68, v2
	v_mov_b32_e32 v69, v2
	v_mov_b32_e32 v70, v2
	v_mov_b32_e32 v71, v2
	v_mov_b32_e32 v72, v2
	v_mov_b32_e32 v73, v2
	v_mov_b32_e32 v74, v2
	v_mov_b32_e32 v75, v2
	v_mov_b32_e32 v76, v2
	v_mov_b32_e32 v77, v2
	v_mov_b32_e32 v82, v2
	v_mov_b32_e32 v83, v2
	v_mov_b32_e32 v84, v2
	v_mov_b32_e32 v85, v2
	v_mov_b32_e32 v90, v2
	v_mov_b32_e32 v91, v2
	v_mov_b32_e32 v92, v2
	v_mov_b32_e32 v93, v2
	v_mov_b32_e32 v98, v2
	v_mov_b32_e32 v99, v2
	v_mov_b32_e32 v100, v2
	v_mov_b32_e32 v101, v2
	v_mov_b32_e32 v106, v2
	v_mov_b32_e32 v107, v2
	v_mov_b32_e32 v108, v2
	v_mov_b32_e32 v109, v2
	v_mov_b32_e32 v114, v2
	v_mov_b32_e32 v115, v2
	v_mov_b32_e32 v116, v2
	v_mov_b32_e32 v117, v2
	v_mov_b32_e32 v78, v2
	v_mov_b32_e32 v79, v2
	v_mov_b32_e32 v80, v2
	v_mov_b32_e32 v81, v2
	v_mov_b32_e32 v86, v2
	v_mov_b32_e32 v87, v2
	v_mov_b32_e32 v88, v2
	v_mov_b32_e32 v89, v2
	v_mov_b32_e32 v94, v2
	v_mov_b32_e32 v95, v2
	v_mov_b32_e32 v96, v2
	v_mov_b32_e32 v97, v2
	v_mov_b32_e32 v102, v2
	v_mov_b32_e32 v103, v2
	v_mov_b32_e32 v104, v2
	v_mov_b32_e32 v105, v2
	v_mov_b32_e32 v110, v2
	v_mov_b32_e32 v111, v2
	v_mov_b32_e32 v112, v2
	v_mov_b32_e32 v113, v2
	v_mov_b32_e32 v118, v2
	v_mov_b32_e32 v119, v2
	v_mov_b32_e32 v120, v2
	v_mov_b32_e32 v121, v2
	v_mov_b32_e32 v122, v2
	v_mov_b32_e32 v123, v2
	v_mov_b32_e32 v124, v2
	v_mov_b32_e32 v125, v2
	v_mov_b32_e32 v126, v2
	v_mov_b32_e32 v127, v2
	v_mov_b32_e32 v128, v2
	v_mov_b32_e32 v129, v2
	s_add_u32 s60, s52, 0xfffe0080
	s_addc_u32 s61, s53, -1
	s_cmp_eq_u32 s77, 4
	s_cselect_b32 s63, s43, s61
	s_cselect_b32 s62, s47, s60
	s_cselect_b32 s61, s45, s76
	s_cselect_b32 s60, s72, s73
.LBB0_325:
	s_add_i32 s78, 0, 0x10000
	v_add_u32_e32 v143, s78, v139
	s_add_i32 s80, 0, 0x14000
	ds_read_b128 v[158:161], v143
	ds_read_b128 v[162:165], v143 offset:1024
	ds_read_b128 v[176:179], v143 offset:2048
	ds_read_b128 v[180:183], v143 offset:3072
	v_add_u32_e32 v143, s80, v139
	ds_read_b128 v[184:187], v143
	ds_read_b128 v[188:191], v143 offset:1024
	ds_read_b128 v[192:195], v143 offset:2048
	ds_read_b128 v[196:199], v143 offset:3072
	v_lshl_add_u64 v[168:169], s[52:53], 0, v[156:157]
	s_add_i32 m0, s26, 0xc000
	ds_read_b128 v[200:203], v141
	ds_read_b128 v[204:207], v141 offset:1024
	ds_read_b128 v[208:211], v141 offset:2048
	ds_read_b128 v[224:227], v141 offset:3072
	ds_read_b128 v[228:231], v141 offset:4096
	ds_read_b128 v[232:235], v141 offset:5120
	ds_read_b128 v[236:239], v141 offset:6144
	ds_read_b128 v[244:247], v141 offset:7168
	global_load_lds_dwordx4 v[168:169], off
	v_lshl_add_u64 v[168:169], s[52:53], 0, v[154:155]
	s_add_i32 m0, s26, 0xe000
	s_nop 0
	global_load_lds_dwordx4 v[168:169], off
	s_waitcnt vmcnt(8)
	s_waitcnt lgkmcnt(0)
	s_barrier
	s_setprio 1
	s_waitcnt lgkmcnt(0)
	v_mfma_f32_16x16x32_bf16 v[126:129], v[158:161], v[200:203], v[126:129]
	v_mfma_f32_16x16x32_bf16 v[122:125], v[176:179], v[200:203], v[122:125]
	v_mfma_f32_16x16x32_bf16 v[118:121], v[158:161], v[208:211], v[118:121]
	v_mfma_f32_16x16x32_bf16 v[110:113], v[176:179], v[208:211], v[110:113]
	v_mfma_f32_16x16x32_bf16 v[102:105], v[158:161], v[228:231], v[102:105]
	v_mfma_f32_16x16x32_bf16 v[94:97], v[176:179], v[228:231], v[94:97]
	v_mfma_f32_16x16x32_bf16 v[86:89], v[158:161], v[236:239], v[86:89]
	v_mfma_f32_16x16x32_bf16 v[78:81], v[176:179], v[236:239], v[78:81]
	v_mfma_f32_16x16x32_bf16 v[126:129], v[162:165], v[204:207], v[126:129]
	v_mfma_f32_16x16x32_bf16 v[122:125], v[180:183], v[204:207], v[122:125]
	v_mfma_f32_16x16x32_bf16 v[118:121], v[162:165], v[224:227], v[118:121]
	v_mfma_f32_16x16x32_bf16 v[110:113], v[180:183], v[224:227], v[110:113]
	v_mfma_f32_16x16x32_bf16 v[102:105], v[162:165], v[232:235], v[102:105]
	v_mfma_f32_16x16x32_bf16 v[94:97], v[180:183], v[232:235], v[94:97]
	v_mfma_f32_16x16x32_bf16 v[86:89], v[162:165], v[244:247], v[86:89]
	v_mfma_f32_16x16x32_bf16 v[78:81], v[180:183], v[244:247], v[78:81]
	s_setprio 0
	s_setprio 1
	v_mfma_f32_16x16x32_bf16 v[114:117], v[184:187], v[200:203], v[114:117]
	v_mfma_f32_16x16x32_bf16 v[106:109], v[192:195], v[200:203], v[106:109]
	v_mfma_f32_16x16x32_bf16 v[98:101], v[184:187], v[208:211], v[98:101]
	v_mfma_f32_16x16x32_bf16 v[90:93], v[192:195], v[208:211], v[90:93]
	v_mfma_f32_16x16x32_bf16 v[82:85], v[184:187], v[228:231], v[82:85]
	v_mfma_f32_16x16x32_bf16 v[74:77], v[192:195], v[228:231], v[74:77]
	v_mfma_f32_16x16x32_bf16 v[70:73], v[184:187], v[236:239], v[70:73]
	v_mfma_f32_16x16x32_bf16 v[66:69], v[192:195], v[236:239], v[66:69]
	v_mfma_f32_16x16x32_bf16 v[114:117], v[188:191], v[204:207], v[114:117]
	v_mfma_f32_16x16x32_bf16 v[106:109], v[196:199], v[204:207], v[106:109]
	v_mfma_f32_16x16x32_bf16 v[98:101], v[188:191], v[224:227], v[98:101]
	v_mfma_f32_16x16x32_bf16 v[90:93], v[196:199], v[224:227], v[90:93]
	v_mfma_f32_16x16x32_bf16 v[82:85], v[188:191], v[232:235], v[82:85]
	v_mfma_f32_16x16x32_bf16 v[74:77], v[196:199], v[232:235], v[74:77]
	v_mfma_f32_16x16x32_bf16 v[70:73], v[188:191], v[244:247], v[70:73]
	v_mfma_f32_16x16x32_bf16 v[66:69], v[196:199], v[244:247], v[66:69]
	s_setprio 0
	s_barrier
	s_add_i32 s78, s78, s23
	v_lshl_add_u64 v[168:169], s[60:61], 0, v[132:133]
	s_mov_b32 m0, s78
	ds_read_b128 v[200:203], v141 offset:16384
	ds_read_b128 v[204:207], v141 offset:17408
	ds_read_b128 v[208:211], v141 offset:18432
	ds_read_b128 v[224:227], v141 offset:19456
	ds_read_b128 v[228:231], v141 offset:20480
	ds_read_b128 v[232:235], v141 offset:21504
	ds_read_b128 v[236:239], v141 offset:22528
	ds_read_b128 v[244:247], v141 offset:23552
	global_load_lds_dwordx4 v[168:169], off
	s_add_i32 m0, s78, 0x2000
	s_add_u32 s78, s60, 0x20000
	v_lshl_add_u64 v[212:213], s[60:61], 0, v[136:137]
	s_addc_u32 s79, s61, 0
	s_add_i32 s80, s80, s23
	global_load_lds_dwordx4 v[212:213], off
	v_lshl_add_u64 v[248:249], s[78:79], 0, v[132:133]
	s_mov_b32 m0, s80
	v_lshl_add_u64 v[170:171], s[62:63], 0, v[134:135]
	global_load_lds_dwordx4 v[248:249], off
	v_lshl_add_u64 v[248:249], s[78:79], 0, v[136:137]
	s_add_i32 m0, s80, 0x2000
	s_nop 0
	global_load_lds_dwordx4 v[248:249], off
	v_lshl_add_u64 v[248:249], s[62:63], 0, v[130:131]
	s_mov_b32 m0, s26
	s_nop 0
	global_load_lds_dwordx4 v[248:249], off
	s_mov_b32 m0, s41
	s_nop 0
	global_load_lds_dwordx4 v[170:171], off
	s_waitcnt vmcnt(8)
	s_waitcnt lgkmcnt(0)
	s_barrier
	s_setprio 1
	s_waitcnt lgkmcnt(0)
	v_mfma_f32_16x16x32_bf16 v[62:65], v[158:161], v[200:203], v[62:65]
	v_mfma_f32_16x16x32_bf16 v[58:61], v[176:179], v[200:203], v[58:61]
	v_mfma_f32_16x16x32_bf16 v[54:57], v[158:161], v[208:211], v[54:57]
	v_mfma_f32_16x16x32_bf16 v[46:49], v[176:179], v[208:211], v[46:49]
	v_mfma_f32_16x16x32_bf16 v[38:41], v[158:161], v[228:231], v[38:41]
	v_mfma_f32_16x16x32_bf16 v[30:33], v[176:179], v[228:231], v[30:33]
	v_mfma_f32_16x16x32_bf16 v[22:25], v[158:161], v[236:239], v[22:25]
	v_mfma_f32_16x16x32_bf16 v[14:17], v[176:179], v[236:239], v[14:17]
	v_mfma_f32_16x16x32_bf16 v[62:65], v[162:165], v[204:207], v[62:65]
	v_mfma_f32_16x16x32_bf16 v[58:61], v[180:183], v[204:207], v[58:61]
	v_mfma_f32_16x16x32_bf16 v[54:57], v[162:165], v[224:227], v[54:57]
	v_mfma_f32_16x16x32_bf16 v[46:49], v[180:183], v[224:227], v[46:49]
	v_mfma_f32_16x16x32_bf16 v[38:41], v[162:165], v[232:235], v[38:41]
	v_mfma_f32_16x16x32_bf16 v[30:33], v[180:183], v[232:235], v[30:33]
	v_mfma_f32_16x16x32_bf16 v[22:25], v[162:165], v[244:247], v[22:25]
	v_mfma_f32_16x16x32_bf16 v[14:17], v[180:183], v[244:247], v[14:17]
	s_setprio 0
	s_setprio 1
	v_mfma_f32_16x16x32_bf16 v[50:53], v[184:187], v[200:203], v[50:53]
	v_mfma_f32_16x16x32_bf16 v[42:45], v[192:195], v[200:203], v[42:45]
	v_mfma_f32_16x16x32_bf16 v[34:37], v[184:187], v[208:211], v[34:37]
	v_mfma_f32_16x16x32_bf16 v[26:29], v[192:195], v[208:211], v[26:29]
	v_mfma_f32_16x16x32_bf16 v[18:21], v[184:187], v[228:231], v[18:21]
	v_mfma_f32_16x16x32_bf16 v[10:13], v[192:195], v[228:231], v[10:13]
	v_mfma_f32_16x16x32_bf16 v[6:9], v[184:187], v[236:239], v[6:9]
	v_mfma_f32_16x16x32_bf16 v[2:5], v[192:195], v[236:239], v[2:5]
	v_mfma_f32_16x16x32_bf16 v[50:53], v[188:191], v[204:207], v[50:53]
	v_mfma_f32_16x16x32_bf16 v[42:45], v[196:199], v[204:207], v[42:45]
	v_mfma_f32_16x16x32_bf16 v[34:37], v[188:191], v[224:227], v[34:37]
	v_mfma_f32_16x16x32_bf16 v[26:29], v[196:199], v[224:227], v[26:29]
	v_mfma_f32_16x16x32_bf16 v[18:21], v[188:191], v[232:235], v[18:21]
	v_mfma_f32_16x16x32_bf16 v[10:13], v[196:199], v[232:235], v[10:13]
	v_mfma_f32_16x16x32_bf16 v[6:9], v[188:191], v[244:247], v[6:9]
	v_mfma_f32_16x16x32_bf16 v[2:5], v[196:199], v[244:247], v[2:5]
	s_setprio 0
	s_barrier
	s_add_i32 s78, 0, 0x18000
	v_add_u32_e32 v143, s78, v139
	s_add_i32 s79, 0, 0x1c000
	ds_read_b128 v[158:161], v143
	ds_read_b128 v[162:165], v143 offset:1024
	ds_read_b128 v[176:179], v143 offset:2048
	ds_read_b128 v[180:183], v143 offset:3072
	v_add_u32_e32 v143, s79, v139
	ds_read_b128 v[184:187], v143
	ds_read_b128 v[188:191], v143 offset:1024
	ds_read_b128 v[192:195], v143 offset:2048
	ds_read_b128 v[196:199], v143 offset:3072
	s_add_u32 s62, s62, 0x20000
	s_addc_u32 s63, s63, 0
	s_mov_b32 m0, s64
	v_lshl_add_u64 v[172:173], s[62:63], 0, v[130:131]
	ds_read_b128 v[200:203], v141 offset:32768
	ds_read_b128 v[204:207], v141 offset:33792
	ds_read_b128 v[208:211], v141 offset:34816
	ds_read_b128 v[224:227], v141 offset:35840
	ds_read_b128 v[228:231], v141 offset:36864
	ds_read_b128 v[232:235], v141 offset:37888
	ds_read_b128 v[236:239], v141 offset:38912
	ds_read_b128 v[244:247], v141 offset:39936
	global_load_lds_dwordx4 v[172:173], off
	v_lshl_add_u64 v[172:173], s[62:63], 0, v[134:135]
	s_mov_b32 m0, s65
	s_nop 0
	global_load_lds_dwordx4 v[172:173], off
	s_waitcnt vmcnt(8)
	s_waitcnt lgkmcnt(0)
	s_barrier
	s_setprio 1
	s_waitcnt lgkmcnt(0)
	v_mfma_f32_16x16x32_bf16 v[126:129], v[158:161], v[200:203], v[126:129]
	v_mfma_f32_16x16x32_bf16 v[122:125], v[176:179], v[200:203], v[122:125]
	v_mfma_f32_16x16x32_bf16 v[118:121], v[158:161], v[208:211], v[118:121]
	v_mfma_f32_16x16x32_bf16 v[110:113], v[176:179], v[208:211], v[110:113]
	v_mfma_f32_16x16x32_bf16 v[102:105], v[158:161], v[228:231], v[102:105]
	v_mfma_f32_16x16x32_bf16 v[94:97], v[176:179], v[228:231], v[94:97]
	v_mfma_f32_16x16x32_bf16 v[86:89], v[158:161], v[236:239], v[86:89]
	v_mfma_f32_16x16x32_bf16 v[78:81], v[176:179], v[236:239], v[78:81]
	v_mfma_f32_16x16x32_bf16 v[126:129], v[162:165], v[204:207], v[126:129]
	v_mfma_f32_16x16x32_bf16 v[122:125], v[180:183], v[204:207], v[122:125]
	v_mfma_f32_16x16x32_bf16 v[118:121], v[162:165], v[224:227], v[118:121]
	v_mfma_f32_16x16x32_bf16 v[110:113], v[180:183], v[224:227], v[110:113]
	v_mfma_f32_16x16x32_bf16 v[102:105], v[162:165], v[232:235], v[102:105]
	v_mfma_f32_16x16x32_bf16 v[94:97], v[180:183], v[232:235], v[94:97]
	v_mfma_f32_16x16x32_bf16 v[86:89], v[162:165], v[244:247], v[86:89]
	v_mfma_f32_16x16x32_bf16 v[78:81], v[180:183], v[244:247], v[78:81]
	s_setprio 0
	s_setprio 1
	v_mfma_f32_16x16x32_bf16 v[114:117], v[184:187], v[200:203], v[114:117]
	v_mfma_f32_16x16x32_bf16 v[106:109], v[192:195], v[200:203], v[106:109]
	v_mfma_f32_16x16x32_bf16 v[98:101], v[184:187], v[208:211], v[98:101]
	v_mfma_f32_16x16x32_bf16 v[90:93], v[192:195], v[208:211], v[90:93]
	v_mfma_f32_16x16x32_bf16 v[82:85], v[184:187], v[228:231], v[82:85]
	v_mfma_f32_16x16x32_bf16 v[74:77], v[192:195], v[228:231], v[74:77]
	v_mfma_f32_16x16x32_bf16 v[70:73], v[184:187], v[236:239], v[70:73]
	v_mfma_f32_16x16x32_bf16 v[66:69], v[192:195], v[236:239], v[66:69]
	v_mfma_f32_16x16x32_bf16 v[114:117], v[188:191], v[204:207], v[114:117]
	v_mfma_f32_16x16x32_bf16 v[106:109], v[196:199], v[204:207], v[106:109]
	v_mfma_f32_16x16x32_bf16 v[98:101], v[188:191], v[224:227], v[98:101]
	v_mfma_f32_16x16x32_bf16 v[90:93], v[196:199], v[224:227], v[90:93]
	v_mfma_f32_16x16x32_bf16 v[82:85], v[188:191], v[232:235], v[82:85]
	v_mfma_f32_16x16x32_bf16 v[74:77], v[196:199], v[232:235], v[74:77]
	v_mfma_f32_16x16x32_bf16 v[70:73], v[188:191], v[244:247], v[70:73]
	v_mfma_f32_16x16x32_bf16 v[66:69], v[196:199], v[244:247], v[66:69]
	s_setprio 0
	s_barrier
	s_add_i32 s62, s78, s23
	v_lshl_add_u64 v[168:169], v[168:169], 0, s[54:55]
	s_mov_b32 m0, s62
	ds_read_b128 v[200:203], v141 offset:49152
	ds_read_b128 v[204:207], v141 offset:50176
	ds_read_b128 v[208:211], v141 offset:51200
	ds_read_b128 v[224:227], v141 offset:52224
	ds_read_b128 v[228:231], v141 offset:53248
	ds_read_b128 v[232:235], v141 offset:54272
	ds_read_b128 v[236:239], v141 offset:55296
	ds_read_b128 v[244:247], v141 offset:56320
	global_load_lds_dwordx4 v[168:169], off
	s_add_i32 m0, s62, 0x2000
	s_add_u32 s60, s60, 0x20080
	v_lshl_add_u64 v[168:169], v[212:213], 0, s[54:55]
	s_addc_u32 s61, s61, 0
	s_add_i32 s62, s79, s23
	global_load_lds_dwordx4 v[168:169], off
	v_lshl_add_u64 v[168:169], s[60:61], 0, v[132:133]
	s_mov_b32 m0, s62
	s_nop 0
	global_load_lds_dwordx4 v[168:169], off
	v_lshl_add_u64 v[168:169], s[60:61], 0, v[136:137]
	s_add_i32 m0, s62, 0x2000
	s_nop 0
	global_load_lds_dwordx4 v[168:169], off
	v_lshl_add_u64 v[168:169], v[248:249], 0, s[54:55]
	s_mov_b32 m0, s68
	s_nop 0
	global_load_lds_dwordx4 v[168:169], off
	v_lshl_add_u64 v[168:169], v[170:171], 0, s[54:55]
	s_mov_b32 m0, s69
	s_nop 0
	global_load_lds_dwordx4 v[168:169], off
	s_add_i32 s77, s77, 2
	s_add_u32 s73, s73, 0x100
	s_addc_u32 s76, s76, 0
	s_add_u32 s52, s52, 0x100
	s_addc_u32 s53, s53, 0
	s_add_u32 s60, s52, 0xfffe0080
	s_addc_u32 s61, s53, -1
	s_cmp_eq_u32 s77, 4
	s_cselect_b32 s63, s43, s61
	s_cselect_b32 s62, s47, s60
	s_cselect_b32 s61, s45, s76
	s_cselect_b32 s60, s72, s73
	s_waitcnt vmcnt(8)
	s_waitcnt lgkmcnt(0)
	s_barrier
	s_setprio 1
	s_waitcnt lgkmcnt(0)
	v_mfma_f32_16x16x32_bf16 v[62:65], v[158:161], v[200:203], v[62:65]
	v_mfma_f32_16x16x32_bf16 v[58:61], v[176:179], v[200:203], v[58:61]
	v_mfma_f32_16x16x32_bf16 v[54:57], v[158:161], v[208:211], v[54:57]
	v_mfma_f32_16x16x32_bf16 v[46:49], v[176:179], v[208:211], v[46:49]
	v_mfma_f32_16x16x32_bf16 v[38:41], v[158:161], v[228:231], v[38:41]
	v_mfma_f32_16x16x32_bf16 v[30:33], v[176:179], v[228:231], v[30:33]
	v_mfma_f32_16x16x32_bf16 v[22:25], v[158:161], v[236:239], v[22:25]
	v_mfma_f32_16x16x32_bf16 v[14:17], v[176:179], v[236:239], v[14:17]
	v_mfma_f32_16x16x32_bf16 v[62:65], v[162:165], v[204:207], v[62:65]
	v_mfma_f32_16x16x32_bf16 v[58:61], v[180:183], v[204:207], v[58:61]
	v_mfma_f32_16x16x32_bf16 v[54:57], v[162:165], v[224:227], v[54:57]
	v_mfma_f32_16x16x32_bf16 v[46:49], v[180:183], v[224:227], v[46:49]
	v_mfma_f32_16x16x32_bf16 v[38:41], v[162:165], v[232:235], v[38:41]
	v_mfma_f32_16x16x32_bf16 v[30:33], v[180:183], v[232:235], v[30:33]
	v_mfma_f32_16x16x32_bf16 v[22:25], v[162:165], v[244:247], v[22:25]
	v_mfma_f32_16x16x32_bf16 v[14:17], v[180:183], v[244:247], v[14:17]
	s_setprio 0
	s_setprio 1
	v_mfma_f32_16x16x32_bf16 v[50:53], v[184:187], v[200:203], v[50:53]
	v_mfma_f32_16x16x32_bf16 v[42:45], v[192:195], v[200:203], v[42:45]
	v_mfma_f32_16x16x32_bf16 v[34:37], v[184:187], v[208:211], v[34:37]
	v_mfma_f32_16x16x32_bf16 v[26:29], v[192:195], v[208:211], v[26:29]
	v_mfma_f32_16x16x32_bf16 v[18:21], v[184:187], v[228:231], v[18:21]
	v_mfma_f32_16x16x32_bf16 v[10:13], v[192:195], v[228:231], v[10:13]
	v_mfma_f32_16x16x32_bf16 v[6:9], v[184:187], v[236:239], v[6:9]
	v_mfma_f32_16x16x32_bf16 v[2:5], v[192:195], v[236:239], v[2:5]
	v_mfma_f32_16x16x32_bf16 v[50:53], v[188:191], v[204:207], v[50:53]
	v_mfma_f32_16x16x32_bf16 v[42:45], v[196:199], v[204:207], v[42:45]
	v_mfma_f32_16x16x32_bf16 v[34:37], v[188:191], v[224:227], v[34:37]
	v_mfma_f32_16x16x32_bf16 v[26:29], v[196:199], v[224:227], v[26:29]
	v_mfma_f32_16x16x32_bf16 v[18:21], v[188:191], v[232:235], v[18:21]
	v_mfma_f32_16x16x32_bf16 v[10:13], v[196:199], v[232:235], v[10:13]
	v_mfma_f32_16x16x32_bf16 v[6:9], v[188:191], v[244:247], v[6:9]
	v_mfma_f32_16x16x32_bf16 v[2:5], v[196:199], v[244:247], v[2:5]
	s_setprio 0
	s_barrier
	s_cmp_gt_u32 s77, 5
	s_cbranch_scc0 .LBB0_325
	s_and_b64 vcc, exec, s[24:25]
	s_cbranch_vccz .LBB0_328
	s_barrier

.LBB0_386:
	s_ashr_i32 s47, s46, 31
	s_lshl_b64 s[48:49], s[46:47], 20
	v_readlane_b32 s45, v254, 61
	s_add_u32 s48, s45, s48
	v_readlane_b32 s45, v254, 62
	s_addc_u32 s49, s45, s49
	s_and_b64 s[50:51], s[38:39], exec
	s_cselect_b32 s47, s49, s61
	s_cselect_b32 s70, s48, s60
	s_ashr_i32 s45, s44, 31
	s_lshl_b64 s[50:51], s[44:45], 20
	s_add_u32 s50, s9, s50
	s_addc_u32 s51, s14, s51
	s_and_b64 s[62:63], s[38:39], exec
	s_cselect_b32 s45, s51, s53
	s_cselect_b32 s71, s50, s52
	s_add_u32 s72, s52, 0x100
	s_addc_u32 s73, s53, 0
	s_add_u32 s52, s60, 0x80080
	v_mov_b32_e32 v2, 0
	s_addc_u32 s53, s61, 0
	s_mov_b32 s76, -2
	v_mov_b32_e32 v3, v2
	v_mov_b32_e32 v4, v2
	v_mov_b32_e32 v5, v2
	v_mov_b32_e32 v6, v2
	v_mov_b32_e32 v7, v2
	v_mov_b32_e32 v8, v2
	v_mov_b32_e32 v9, v2
	v_mov_b32_e32 v10, v2
	v_mov_b32_e32 v11, v2
	v_mov_b32_e32 v12, v2
	v_mov_b32_e32 v13, v2
	v_mov_b32_e32 v14, v2
	v_mov_b32_e32 v15, v2
	v_mov_b32_e32 v16, v2
	v_mov_b32_e32 v17, v2
	v_mov_b32_e32 v18, v2
	v_mov_b32_e32 v19, v2
	v_mov_b32_e32 v20, v2
	v_mov_b32_e32 v21, v2
	v_mov_b32_e32 v26, v2
	v_mov_b32_e32 v27, v2
	v_mov_b32_e32 v28, v2
	v_mov_b32_e32 v29, v2
	v_mov_b32_e32 v34, v2
	v_mov_b32_e32 v35, v2
	v_mov_b32_e32 v36, v2
	v_mov_b32_e32 v37, v2
	v_mov_b32_e32 v42, v2
	v_mov_b32_e32 v43, v2
	v_mov_b32_e32 v44, v2
	v_mov_b32_e32 v45, v2
	v_mov_b32_e32 v22, v2
	v_mov_b32_e32 v23, v2
	v_mov_b32_e32 v24, v2
	v_mov_b32_e32 v25, v2
	v_mov_b32_e32 v30, v2
	v_mov_b32_e32 v31, v2
	v_mov_b32_e32 v32, v2
	v_mov_b32_e32 v33, v2
	v_mov_b32_e32 v38, v2
	v_mov_b32_e32 v39, v2
	v_mov_b32_e32 v40, v2
	v_mov_b32_e32 v41, v2
	v_mov_b32_e32 v46, v2
	v_mov_b32_e32 v47, v2
	v_mov_b32_e32 v48, v2
	v_mov_b32_e32 v49, v2
	v_mov_b32_e32 v50, v2
	v_mov_b32_e32 v51, v2
	v_mov_b32_e32 v52, v2
	v_mov_b32_e32 v53, v2
	v_mov_b32_e32 v54, v2
	v_mov_b32_e32 v55, v2
	v_mov_b32_e32 v56, v2
	v_mov_b32_e32 v57, v2
	v_mov_b32_e32 v58, v2
	v_mov_b32_e32 v59, v2
	v_mov_b32_e32 v60, v2
	v_mov_b32_e32 v61, v2
	v_mov_b32_e32 v62, v2
	v_mov_b32_e32 v63, v2
	v_mov_b32_e32 v64, v2
	v_mov_b32_e32 v65, v2
	v_mov_b32_e32 v66, v2
	v_mov_b32_e32 v67, v2
	v_mov_b32_e32 v68, v2
	v_mov_b32_e32 v69, v2
	v_mov_b32_e32 v70, v2
	v_mov_b32_e32 v71, v2
	v_mov_b32_e32 v72, v2
	v_mov_b32_e32 v73, v2
	v_mov_b32_e32 v74, v2
	v_mov_b32_e32 v75, v2
	v_mov_b32_e32 v76, v2
	v_mov_b32_e32 v77, v2
	v_mov_b32_e32 v78, v2
	v_mov_b32_e32 v79, v2
	v_mov_b32_e32 v80, v2
	v_mov_b32_e32 v81, v2
	v_mov_b32_e32 v82, v2
	v_mov_b32_e32 v83, v2
	v_mov_b32_e32 v84, v2
	v_mov_b32_e32 v85, v2
	v_mov_b32_e32 v90, v2
	v_mov_b32_e32 v91, v2
	v_mov_b32_e32 v92, v2
	v_mov_b32_e32 v93, v2
	v_mov_b32_e32 v98, v2
	v_mov_b32_e32 v99, v2
	v_mov_b32_e32 v100, v2
	v_mov_b32_e32 v101, v2
	v_mov_b32_e32 v106, v2
	v_mov_b32_e32 v107, v2
	v_mov_b32_e32 v108, v2
	v_mov_b32_e32 v109, v2
	v_mov_b32_e32 v86, v2
	v_mov_b32_e32 v87, v2
	v_mov_b32_e32 v88, v2
	v_mov_b32_e32 v89, v2
	v_mov_b32_e32 v94, v2
	v_mov_b32_e32 v95, v2
	v_mov_b32_e32 v96, v2
	v_mov_b32_e32 v97, v2
	v_mov_b32_e32 v102, v2
	v_mov_b32_e32 v103, v2
	v_mov_b32_e32 v104, v2
	v_mov_b32_e32 v105, v2
	v_mov_b32_e32 v110, v2
	v_mov_b32_e32 v111, v2
	v_mov_b32_e32 v112, v2
	v_mov_b32_e32 v113, v2
	v_mov_b32_e32 v114, v2
	v_mov_b32_e32 v115, v2
	v_mov_b32_e32 v116, v2
	v_mov_b32_e32 v117, v2
	v_mov_b32_e32 v118, v2
	v_mov_b32_e32 v119, v2
	v_mov_b32_e32 v120, v2
	v_mov_b32_e32 v121, v2
	v_mov_b32_e32 v122, v2
	v_mov_b32_e32 v123, v2
	v_mov_b32_e32 v124, v2
	v_mov_b32_e32 v125, v2
	v_mov_b32_e32 v126, v2
	v_mov_b32_e32 v127, v2
	v_mov_b32_e32 v128, v2
	v_mov_b32_e32 v129, v2
	s_add_u32 s60, s52, 0xfff80080
	s_addc_u32 s61, s53, -1
	s_cmp_eq_u32 s76, 28
	s_cselect_b32 s63, s47, s61
	s_cselect_b32 s62, s70, s60
	s_cselect_b32 s61, s45, s73
	s_cselect_b32 s60, s71, s72
.LBB0_387:
	s_add_i32 s77, 0, 0x10000
	v_add_u32_e32 v141, s77, v139
	s_add_i32 s80, 0, 0x14000
	ds_read_b128 v[142:145], v141
	ds_read_b128 v[146:149], v141 offset:1024
	ds_read_b128 v[150:153], v141 offset:2048
	ds_read_b128 v[154:157], v141 offset:3072
	v_add_u32_e32 v141, s80, v139
	ds_read_b128 v[158:161], v141
	ds_read_b128 v[162:165], v141 offset:1024
	ds_read_b128 v[176:179], v141 offset:2048
	ds_read_b128 v[180:183], v141 offset:3072
	v_lshl_add_u64 v[168:169], s[52:53], 0, v[136:137]
	s_add_i32 m0, s23, 0xc000
	ds_read_b128 v[184:187], v140
	ds_read_b128 v[188:191], v140 offset:1024
	ds_read_b128 v[192:195], v140 offset:2048
	ds_read_b128 v[196:199], v140 offset:3072
	ds_read_b128 v[200:203], v140 offset:4096
	ds_read_b128 v[204:207], v140 offset:5120
	ds_read_b128 v[208:211], v140 offset:6144
	ds_read_b128 v[224:227], v140 offset:7168
	global_load_lds_dwordx4 v[168:169], off
	v_lshl_add_u64 v[168:169], s[52:53], 0, v[134:135]
	s_add_i32 m0, s23, 0xe000
	s_nop 0
	global_load_lds_dwordx4 v[168:169], off
	s_waitcnt vmcnt(8)
	s_waitcnt lgkmcnt(0)
	s_barrier
	s_setprio 1
	s_waitcnt lgkmcnt(0)
	v_mfma_f32_16x16x32_bf16 v[126:129], v[142:145], v[184:187], v[126:129]
	v_mfma_f32_16x16x32_bf16 v[122:125], v[150:153], v[184:187], v[122:125]
	v_mfma_f32_16x16x32_bf16 v[118:121], v[142:145], v[192:195], v[118:121]
	v_mfma_f32_16x16x32_bf16 v[114:117], v[150:153], v[192:195], v[114:117]
	v_mfma_f32_16x16x32_bf16 v[110:113], v[142:145], v[200:203], v[110:113]
	v_mfma_f32_16x16x32_bf16 v[102:105], v[150:153], v[200:203], v[102:105]
	v_mfma_f32_16x16x32_bf16 v[94:97], v[142:145], v[208:211], v[94:97]
	v_mfma_f32_16x16x32_bf16 v[86:89], v[150:153], v[208:211], v[86:89]
	v_mfma_f32_16x16x32_bf16 v[126:129], v[146:149], v[188:191], v[126:129]
	v_mfma_f32_16x16x32_bf16 v[122:125], v[154:157], v[188:191], v[122:125]
	v_mfma_f32_16x16x32_bf16 v[118:121], v[146:149], v[196:199], v[118:121]
	v_mfma_f32_16x16x32_bf16 v[114:117], v[154:157], v[196:199], v[114:117]
	v_mfma_f32_16x16x32_bf16 v[110:113], v[146:149], v[204:207], v[110:113]
	v_mfma_f32_16x16x32_bf16 v[102:105], v[154:157], v[204:207], v[102:105]
	v_mfma_f32_16x16x32_bf16 v[94:97], v[146:149], v[224:227], v[94:97]
	v_mfma_f32_16x16x32_bf16 v[86:89], v[154:157], v[224:227], v[86:89]
	s_setprio 0
	s_setprio 1
	v_mfma_f32_16x16x32_bf16 v[106:109], v[158:161], v[184:187], v[106:109]
	v_mfma_f32_16x16x32_bf16 v[98:101], v[176:179], v[184:187], v[98:101]
	v_mfma_f32_16x16x32_bf16 v[90:93], v[158:161], v[192:195], v[90:93]
	v_mfma_f32_16x16x32_bf16 v[82:85], v[176:179], v[192:195], v[82:85]
	v_mfma_f32_16x16x32_bf16 v[78:81], v[158:161], v[200:203], v[78:81]
	v_mfma_f32_16x16x32_bf16 v[74:77], v[176:179], v[200:203], v[74:77]
	v_mfma_f32_16x16x32_bf16 v[70:73], v[158:161], v[208:211], v[70:73]
	v_mfma_f32_16x16x32_bf16 v[66:69], v[176:179], v[208:211], v[66:69]
	v_mfma_f32_16x16x32_bf16 v[106:109], v[162:165], v[188:191], v[106:109]
	v_mfma_f32_16x16x32_bf16 v[98:101], v[180:183], v[188:191], v[98:101]
	v_mfma_f32_16x16x32_bf16 v[90:93], v[162:165], v[196:199], v[90:93]
	v_mfma_f32_16x16x32_bf16 v[82:85], v[180:183], v[196:199], v[82:85]
	v_mfma_f32_16x16x32_bf16 v[78:81], v[162:165], v[204:207], v[78:81]
	v_mfma_f32_16x16x32_bf16 v[74:77], v[180:183], v[204:207], v[74:77]
	v_mfma_f32_16x16x32_bf16 v[70:73], v[162:165], v[224:227], v[70:73]
	v_mfma_f32_16x16x32_bf16 v[66:69], v[180:183], v[224:227], v[66:69]
	s_setprio 0
	s_barrier
	s_add_i32 s77, s77, s17
	v_lshl_add_u64 v[168:169], s[60:61], 0, v[132:133]
	s_mov_b32 m0, s77
	ds_read_b128 v[184:187], v140 offset:16384
	ds_read_b128 v[188:191], v140 offset:17408
	ds_read_b128 v[192:195], v140 offset:18432
	ds_read_b128 v[196:199], v140 offset:19456
	ds_read_b128 v[200:203], v140 offset:20480
	ds_read_b128 v[204:207], v140 offset:21504
	ds_read_b128 v[208:211], v140 offset:22528
	ds_read_b128 v[224:227], v140 offset:23552
	global_load_lds_dwordx4 v[168:169], off
	s_add_i32 m0, s77, 0x2000
	s_add_u32 s78, s60, 0x80000
	v_lshl_add_u64 v[212:213], s[60:61], 0, v[130:131]
	s_addc_u32 s79, s61, 0
	s_add_i32 s77, s80, s17
	global_load_lds_dwordx4 v[212:213], off
	v_lshl_add_u64 v[228:229], s[78:79], 0, v[132:133]
	s_mov_b32 m0, s77
	v_lshl_add_u64 v[230:231], s[62:63], 0, v[130:131]
	global_load_lds_dwordx4 v[228:229], off
	v_lshl_add_u64 v[228:229], s[78:79], 0, v[130:131]
	s_add_i32 m0, s77, 0x2000
	s_nop 0
	global_load_lds_dwordx4 v[228:229], off
	v_lshl_add_u64 v[228:229], s[62:63], 0, v[132:133]
	s_mov_b32 m0, s23
	s_nop 0
	global_load_lds_dwordx4 v[228:229], off
	s_mov_b32 m0, s41
	s_nop 0
	global_load_lds_dwordx4 v[230:231], off
	s_waitcnt vmcnt(8)
	s_waitcnt lgkmcnt(0)
	s_barrier
	s_setprio 1
	s_waitcnt lgkmcnt(0)
	v_mfma_f32_16x16x32_bf16 v[62:65], v[142:145], v[184:187], v[62:65]
	v_mfma_f32_16x16x32_bf16 v[58:61], v[150:153], v[184:187], v[58:61]
	v_mfma_f32_16x16x32_bf16 v[54:57], v[142:145], v[192:195], v[54:57]
	v_mfma_f32_16x16x32_bf16 v[50:53], v[150:153], v[192:195], v[50:53]
	v_mfma_f32_16x16x32_bf16 v[46:49], v[142:145], v[200:203], v[46:49]
	v_mfma_f32_16x16x32_bf16 v[38:41], v[150:153], v[200:203], v[38:41]
	v_mfma_f32_16x16x32_bf16 v[30:33], v[142:145], v[208:211], v[30:33]
	v_mfma_f32_16x16x32_bf16 v[22:25], v[150:153], v[208:211], v[22:25]
	v_mfma_f32_16x16x32_bf16 v[62:65], v[146:149], v[188:191], v[62:65]
	v_mfma_f32_16x16x32_bf16 v[58:61], v[154:157], v[188:191], v[58:61]
	v_mfma_f32_16x16x32_bf16 v[54:57], v[146:149], v[196:199], v[54:57]
	v_mfma_f32_16x16x32_bf16 v[50:53], v[154:157], v[196:199], v[50:53]
	v_mfma_f32_16x16x32_bf16 v[46:49], v[146:149], v[204:207], v[46:49]
	v_mfma_f32_16x16x32_bf16 v[38:41], v[154:157], v[204:207], v[38:41]
	v_mfma_f32_16x16x32_bf16 v[30:33], v[146:149], v[224:227], v[30:33]
	v_mfma_f32_16x16x32_bf16 v[22:25], v[154:157], v[224:227], v[22:25]
	s_setprio 0
	s_setprio 1
	v_mfma_f32_16x16x32_bf16 v[42:45], v[158:161], v[184:187], v[42:45]
	v_mfma_f32_16x16x32_bf16 v[34:37], v[176:179], v[184:187], v[34:37]
	v_mfma_f32_16x16x32_bf16 v[26:29], v[158:161], v[192:195], v[26:29]
	v_mfma_f32_16x16x32_bf16 v[18:21], v[176:179], v[192:195], v[18:21]
	v_mfma_f32_16x16x32_bf16 v[14:17], v[158:161], v[200:203], v[14:17]
	v_mfma_f32_16x16x32_bf16 v[10:13], v[176:179], v[200:203], v[10:13]
	v_mfma_f32_16x16x32_bf16 v[6:9], v[158:161], v[208:211], v[6:9]
	v_mfma_f32_16x16x32_bf16 v[2:5], v[176:179], v[208:211], v[2:5]
	v_mfma_f32_16x16x32_bf16 v[42:45], v[162:165], v[188:191], v[42:45]
	v_mfma_f32_16x16x32_bf16 v[34:37], v[180:183], v[188:191], v[34:37]
	v_mfma_f32_16x16x32_bf16 v[26:29], v[162:165], v[196:199], v[26:29]
	v_mfma_f32_16x16x32_bf16 v[18:21], v[180:183], v[196:199], v[18:21]
	v_mfma_f32_16x16x32_bf16 v[14:17], v[162:165], v[204:207], v[14:17]
	v_mfma_f32_16x16x32_bf16 v[10:13], v[180:183], v[204:207], v[10:13]
	v_mfma_f32_16x16x32_bf16 v[6:9], v[162:165], v[224:227], v[6:9]
	v_mfma_f32_16x16x32_bf16 v[2:5], v[180:183], v[224:227], v[2:5]
	s_setprio 0
	s_barrier
	s_add_i32 s77, 0, 0x18000
	v_add_u32_e32 v141, s77, v139
	s_add_i32 s78, 0, 0x1c000
	ds_read_b128 v[142:145], v141
	ds_read_b128 v[146:149], v141 offset:1024
	ds_read_b128 v[150:153], v141 offset:2048
	ds_read_b128 v[154:157], v141 offset:3072
	v_add_u32_e32 v141, s78, v139
	ds_read_b128 v[158:161], v141
	ds_read_b128 v[162:165], v141 offset:1024
	ds_read_b128 v[176:179], v141 offset:2048
	ds_read_b128 v[180:183], v141 offset:3072
	s_add_u32 s62, s62, 0x80000
	s_addc_u32 s63, s63, 0
	s_mov_b32 m0, s64
	v_lshl_add_u64 v[232:233], s[62:63], 0, v[132:133]
	ds_read_b128 v[184:187], v140 offset:32768
	ds_read_b128 v[188:191], v140 offset:33792
	ds_read_b128 v[192:195], v140 offset:34816
	ds_read_b128 v[196:199], v140 offset:35840
	ds_read_b128 v[200:203], v140 offset:36864
	ds_read_b128 v[204:207], v140 offset:37888
	ds_read_b128 v[208:211], v140 offset:38912
	ds_read_b128 v[224:227], v140 offset:39936
	global_load_lds_dwordx4 v[232:233], off
	v_lshl_add_u64 v[232:233], s[62:63], 0, v[130:131]
	s_mov_b32 m0, s65
	s_nop 0
	global_load_lds_dwordx4 v[232:233], off
	s_waitcnt vmcnt(8)
	s_waitcnt lgkmcnt(0)
	s_barrier
	s_setprio 1
	s_waitcnt lgkmcnt(0)
	v_mfma_f32_16x16x32_bf16 v[126:129], v[142:145], v[184:187], v[126:129]
	v_mfma_f32_16x16x32_bf16 v[122:125], v[150:153], v[184:187], v[122:125]
	v_mfma_f32_16x16x32_bf16 v[118:121], v[142:145], v[192:195], v[118:121]
	v_mfma_f32_16x16x32_bf16 v[114:117], v[150:153], v[192:195], v[114:117]
	v_mfma_f32_16x16x32_bf16 v[110:113], v[142:145], v[200:203], v[110:113]
	v_mfma_f32_16x16x32_bf16 v[102:105], v[150:153], v[200:203], v[102:105]
	v_mfma_f32_16x16x32_bf16 v[94:97], v[142:145], v[208:211], v[94:97]
	v_mfma_f32_16x16x32_bf16 v[86:89], v[150:153], v[208:211], v[86:89]
	v_mfma_f32_16x16x32_bf16 v[126:129], v[146:149], v[188:191], v[126:129]
	v_mfma_f32_16x16x32_bf16 v[122:125], v[154:157], v[188:191], v[122:125]
	v_mfma_f32_16x16x32_bf16 v[118:121], v[146:149], v[196:199], v[118:121]
	v_mfma_f32_16x16x32_bf16 v[114:117], v[154:157], v[196:199], v[114:117]
	v_mfma_f32_16x16x32_bf16 v[110:113], v[146:149], v[204:207], v[110:113]
	v_mfma_f32_16x16x32_bf16 v[102:105], v[154:157], v[204:207], v[102:105]
	v_mfma_f32_16x16x32_bf16 v[94:97], v[146:149], v[224:227], v[94:97]
	v_mfma_f32_16x16x32_bf16 v[86:89], v[154:157], v[224:227], v[86:89]
	s_setprio 0
	s_setprio 1
	v_mfma_f32_16x16x32_bf16 v[106:109], v[158:161], v[184:187], v[106:109]
	v_mfma_f32_16x16x32_bf16 v[98:101], v[176:179], v[184:187], v[98:101]
	v_mfma_f32_16x16x32_bf16 v[90:93], v[158:161], v[192:195], v[90:93]
	v_mfma_f32_16x16x32_bf16 v[82:85], v[176:179], v[192:195], v[82:85]
	v_mfma_f32_16x16x32_bf16 v[78:81], v[158:161], v[200:203], v[78:81]
	v_mfma_f32_16x16x32_bf16 v[74:77], v[176:179], v[200:203], v[74:77]
	v_mfma_f32_16x16x32_bf16 v[70:73], v[158:161], v[208:211], v[70:73]
	v_mfma_f32_16x16x32_bf16 v[66:69], v[176:179], v[208:211], v[66:69]
	v_mfma_f32_16x16x32_bf16 v[106:109], v[162:165], v[188:191], v[106:109]
	v_mfma_f32_16x16x32_bf16 v[98:101], v[180:183], v[188:191], v[98:101]
	v_mfma_f32_16x16x32_bf16 v[90:93], v[162:165], v[196:199], v[90:93]
	v_mfma_f32_16x16x32_bf16 v[82:85], v[180:183], v[196:199], v[82:85]
	v_mfma_f32_16x16x32_bf16 v[78:81], v[162:165], v[204:207], v[78:81]
	v_mfma_f32_16x16x32_bf16 v[74:77], v[180:183], v[204:207], v[74:77]
	v_mfma_f32_16x16x32_bf16 v[70:73], v[162:165], v[224:227], v[70:73]
	v_mfma_f32_16x16x32_bf16 v[66:69], v[180:183], v[224:227], v[66:69]
	s_setprio 0
	s_barrier
	s_add_i32 s62, s77, s17
	v_lshl_add_u64 v[168:169], v[168:169], 0, s[54:55]
	s_mov_b32 m0, s62
	ds_read_b128 v[184:187], v140 offset:49152
	ds_read_b128 v[188:191], v140 offset:50176
	ds_read_b128 v[192:195], v140 offset:51200
	ds_read_b128 v[196:199], v140 offset:52224
	ds_read_b128 v[200:203], v140 offset:53248
	ds_read_b128 v[204:207], v140 offset:54272
	ds_read_b128 v[208:211], v140 offset:55296
	ds_read_b128 v[224:227], v140 offset:56320
	global_load_lds_dwordx4 v[168:169], off
	s_add_i32 m0, s62, 0x2000
	s_add_u32 s60, s60, 0x80080
	v_lshl_add_u64 v[168:169], v[212:213], 0, s[54:55]
	s_addc_u32 s61, s61, 0
	s_add_i32 s62, s78, s17
	global_load_lds_dwordx4 v[168:169], off
	v_lshl_add_u64 v[168:169], s[60:61], 0, v[132:133]
	s_mov_b32 m0, s62
	s_nop 0
	global_load_lds_dwordx4 v[168:169], off
	v_lshl_add_u64 v[168:169], s[60:61], 0, v[130:131]
	s_add_i32 m0, s62, 0x2000
	s_nop 0
	global_load_lds_dwordx4 v[168:169], off
	v_lshl_add_u64 v[168:169], v[228:229], 0, s[54:55]
	s_mov_b32 m0, s66
	s_nop 0
	global_load_lds_dwordx4 v[168:169], off
	v_lshl_add_u64 v[168:169], v[230:231], 0, s[54:55]
	s_mov_b32 m0, s67
	s_nop 0
	global_load_lds_dwordx4 v[168:169], off
	s_add_i32 s76, s76, 2
	s_add_u32 s72, s72, 0x100
	s_addc_u32 s73, s73, 0
	s_add_u32 s52, s52, 0x100
	s_addc_u32 s53, s53, 0
	s_add_u32 s60, s52, 0xfff80080
	s_addc_u32 s61, s53, -1
	s_cmp_eq_u32 s76, 28
	s_cselect_b32 s63, s47, s61
	s_cselect_b32 s62, s70, s60
	s_cselect_b32 s61, s45, s73
	s_cselect_b32 s60, s71, s72
	s_waitcnt vmcnt(8)
	s_waitcnt lgkmcnt(0)
	s_barrier
	s_setprio 1
	s_waitcnt lgkmcnt(0)
	v_mfma_f32_16x16x32_bf16 v[62:65], v[142:145], v[184:187], v[62:65]
	v_mfma_f32_16x16x32_bf16 v[58:61], v[150:153], v[184:187], v[58:61]
	v_mfma_f32_16x16x32_bf16 v[54:57], v[142:145], v[192:195], v[54:57]
	v_mfma_f32_16x16x32_bf16 v[50:53], v[150:153], v[192:195], v[50:53]
	v_mfma_f32_16x16x32_bf16 v[46:49], v[142:145], v[200:203], v[46:49]
	v_mfma_f32_16x16x32_bf16 v[38:41], v[150:153], v[200:203], v[38:41]
	v_mfma_f32_16x16x32_bf16 v[30:33], v[142:145], v[208:211], v[30:33]
	v_mfma_f32_16x16x32_bf16 v[22:25], v[150:153], v[208:211], v[22:25]
	v_mfma_f32_16x16x32_bf16 v[62:65], v[146:149], v[188:191], v[62:65]
	v_mfma_f32_16x16x32_bf16 v[58:61], v[154:157], v[188:191], v[58:61]
	v_mfma_f32_16x16x32_bf16 v[54:57], v[146:149], v[196:199], v[54:57]
	v_mfma_f32_16x16x32_bf16 v[50:53], v[154:157], v[196:199], v[50:53]
	v_mfma_f32_16x16x32_bf16 v[46:49], v[146:149], v[204:207], v[46:49]
	v_mfma_f32_16x16x32_bf16 v[38:41], v[154:157], v[204:207], v[38:41]
	v_mfma_f32_16x16x32_bf16 v[30:33], v[146:149], v[224:227], v[30:33]
	v_mfma_f32_16x16x32_bf16 v[22:25], v[154:157], v[224:227], v[22:25]
	s_setprio 0
	s_setprio 1
	v_mfma_f32_16x16x32_bf16 v[42:45], v[158:161], v[184:187], v[42:45]
	v_mfma_f32_16x16x32_bf16 v[34:37], v[176:179], v[184:187], v[34:37]
	v_mfma_f32_16x16x32_bf16 v[26:29], v[158:161], v[192:195], v[26:29]
	v_mfma_f32_16x16x32_bf16 v[18:21], v[176:179], v[192:195], v[18:21]
	v_mfma_f32_16x16x32_bf16 v[14:17], v[158:161], v[200:203], v[14:17]
	v_mfma_f32_16x16x32_bf16 v[10:13], v[176:179], v[200:203], v[10:13]
	v_mfma_f32_16x16x32_bf16 v[6:9], v[158:161], v[208:211], v[6:9]
	v_mfma_f32_16x16x32_bf16 v[2:5], v[176:179], v[208:211], v[2:5]
	v_mfma_f32_16x16x32_bf16 v[42:45], v[162:165], v[188:191], v[42:45]
	v_mfma_f32_16x16x32_bf16 v[34:37], v[180:183], v[188:191], v[34:37]
	v_mfma_f32_16x16x32_bf16 v[26:29], v[162:165], v[196:199], v[26:29]
	v_mfma_f32_16x16x32_bf16 v[18:21], v[180:183], v[196:199], v[18:21]
	v_mfma_f32_16x16x32_bf16 v[14:17], v[162:165], v[204:207], v[14:17]
	v_mfma_f32_16x16x32_bf16 v[10:13], v[180:183], v[204:207], v[10:13]
	v_mfma_f32_16x16x32_bf16 v[6:9], v[162:165], v[224:227], v[6:9]
	v_mfma_f32_16x16x32_bf16 v[2:5], v[180:183], v[224:227], v[2:5]
	s_setprio 0
	s_barrier
	s_cmp_gt_u32 s76, 29
	s_cbranch_scc0 .LBB0_387
	s_and_b64 vcc, exec, s[42:43]
	s_cbranch_vccz .LBB0_390
	s_barrier
